# attention preamble: rel-bias max and LDS table fill issue all loads at once (was ~37 dependent L2 round trips per wave); MLA-up meta rows: all 32 loads hoisted
# baseline (speedup 1.0000x reference)
.LBB0_834:
	s_lshl_b32 s0, s5, 9
	s_and_b32 s0, s0, 0x3e000
	s_cmp_gt_i32 s4, 31
	v_lshl_or_b32 v1, v18, 1, s0
	s_cselect_b64 s[0:1], -1, 0
	s_and_b64 s[8:9], s[0:1], exec
	s_mov_b32 s8, 0x1a00000
	s_cselect_b32 s8, s8, 0x19c0000
	v_or_b32_e32 v0, s8, v1
	v_mov_b32_e32 v1, v149
	v_lshl_add_u64 v[12:13], v[8:9], 0, v[0:1]
	v_mov_b64_e32 v[14:15], v[10:11]
	global_load_dwordx4 v[64:67], v[6:7], off offset:-32
	global_load_dwordx4 v[68:71], v[6:7], off offset:-16
	global_load_dwordx4 v[72:75], v[6:7], off
	global_load_dwordx4 v[76:79], v[6:7], off offset:16
	global_load_dwordx4 v[80:83], v[6:7], off offset:32
	global_load_dwordx4 v[84:87], v[6:7], off offset:48
	global_load_dwordx4 v[88:91], v[6:7], off offset:64
	global_load_dwordx4 v[92:95], v[6:7], off offset:80
	global_load_dwordx4 v[96:99], v[6:7], off offset:96
	global_load_dwordx4 v[100:103], v[6:7], off offset:112
	global_load_dwordx4 v[104:107], v[6:7], off offset:128
	global_load_dwordx4 v[108:111], v[6:7], off offset:144
	global_load_dwordx4 v[112:115], v[6:7], off offset:160
	global_load_dwordx4 v[152:155], v[6:7], off offset:176
	global_load_dwordx4 v[156:159], v[6:7], off offset:192
	global_load_dwordx4 v[160:163], v[6:7], off offset:208
	global_load_dwordx4 v[164:167], v[14:15], off offset:-128
	global_load_dwordx4 v[196:199], v[12:13], off offset:-128
	global_load_dwordx4 v[168:171], v[14:15], off offset:-64
	global_load_dwordx4 v[200:203], v[12:13], off offset:-64
	global_load_dwordx4 v[172:175], v[14:15], off
	global_load_dwordx4 v[220:223], v[12:13], off
	global_load_dwordx4 v[176:179], v[14:15], off offset:64
	global_load_dwordx4 v[224:227], v[12:13], off offset:64
	global_load_dwordx4 v[180:183], v[14:15], off offset:128
	global_load_dwordx4 v[228:231], v[12:13], off offset:128
	global_load_dwordx4 v[184:187], v[14:15], off offset:192
	global_load_dwordx4 v[132:135], v[12:13], off offset:192
	global_load_dwordx4 v[188:191], v[14:15], off offset:256
	global_load_dwordx4 v[136:139], v[12:13], off offset:256
	global_load_dwordx4 v[192:195], v[14:15], off offset:320
	global_load_dwordx4 v[144:147], v[12:13], off offset:320
	v_mov_b32_e32 v2, 0
	s_waitcnt vmcnt(31)
	v_pk_mul_f32 v[64:65], v[64:65], v[64:65]
	v_pk_mul_f32 v[66:67], v[66:67], v[66:67]
	v_add_f32_e32 v64, v65, v64
	v_add_f32_e32 v66, v66, v67
	v_add_f32_e32 v64, v64, v66
	v_add_f32_e32 v2, v2, v64
	s_waitcnt vmcnt(30)
	v_pk_mul_f32 v[68:69], v[68:69], v[68:69]
	v_pk_mul_f32 v[70:71], v[70:71], v[70:71]
	v_add_f32_e32 v68, v69, v68
	v_add_f32_e32 v70, v70, v71
	v_add_f32_e32 v68, v68, v70
	v_add_f32_e32 v2, v2, v68
	s_waitcnt vmcnt(29)
	v_pk_mul_f32 v[72:73], v[72:73], v[72:73]
	v_pk_mul_f32 v[74:75], v[74:75], v[74:75]
	v_add_f32_e32 v72, v73, v72
	v_add_f32_e32 v74, v74, v75
	v_add_f32_e32 v72, v72, v74
	v_add_f32_e32 v2, v2, v72
	s_waitcnt vmcnt(28)
	v_pk_mul_f32 v[76:77], v[76:77], v[76:77]
	v_pk_mul_f32 v[78:79], v[78:79], v[78:79]
	v_add_f32_e32 v76, v77, v76
	v_add_f32_e32 v78, v78, v79
	v_add_f32_e32 v76, v76, v78
	v_add_f32_e32 v2, v2, v76
	s_waitcnt vmcnt(27)
	v_pk_mul_f32 v[80:81], v[80:81], v[80:81]
	v_pk_mul_f32 v[82:83], v[82:83], v[82:83]
	v_add_f32_e32 v80, v81, v80
	v_add_f32_e32 v82, v82, v83
	v_add_f32_e32 v80, v80, v82
	v_add_f32_e32 v2, v2, v80
	s_waitcnt vmcnt(26)
	v_pk_mul_f32 v[84:85], v[84:85], v[84:85]
	v_pk_mul_f32 v[86:87], v[86:87], v[86:87]
	v_add_f32_e32 v84, v85, v84
	v_add_f32_e32 v86, v86, v87
	v_add_f32_e32 v84, v84, v86
	v_add_f32_e32 v2, v2, v84
	s_waitcnt vmcnt(25)
	v_pk_mul_f32 v[88:89], v[88:89], v[88:89]
	v_pk_mul_f32 v[90:91], v[90:91], v[90:91]
	v_add_f32_e32 v88, v89, v88
	v_add_f32_e32 v90, v90, v91
	v_add_f32_e32 v88, v88, v90
	v_add_f32_e32 v2, v2, v88
	s_waitcnt vmcnt(24)
	v_pk_mul_f32 v[92:93], v[92:93], v[92:93]
	v_pk_mul_f32 v[94:95], v[94:95], v[94:95]
	v_add_f32_e32 v92, v93, v92
	v_add_f32_e32 v94, v94, v95
	v_add_f32_e32 v92, v92, v94
	v_add_f32_e32 v2, v2, v92
	s_waitcnt vmcnt(23)
	v_pk_mul_f32 v[96:97], v[96:97], v[96:97]
	v_pk_mul_f32 v[98:99], v[98:99], v[98:99]
	v_add_f32_e32 v96, v97, v96
	v_add_f32_e32 v98, v98, v99
	v_add_f32_e32 v96, v96, v98
	v_add_f32_e32 v2, v2, v96
	s_waitcnt vmcnt(22)
	v_pk_mul_f32 v[100:101], v[100:101], v[100:101]
	v_pk_mul_f32 v[102:103], v[102:103], v[102:103]
	v_add_f32_e32 v100, v101, v100
	v_add_f32_e32 v102, v102, v103
	v_add_f32_e32 v100, v100, v102
	v_add_f32_e32 v2, v2, v100
	s_waitcnt vmcnt(21)
	v_pk_mul_f32 v[104:105], v[104:105], v[104:105]
	v_pk_mul_f32 v[106:107], v[106:107], v[106:107]
	v_add_f32_e32 v104, v105, v104
	v_add_f32_e32 v106, v106, v107
	v_add_f32_e32 v104, v104, v106
	v_add_f32_e32 v2, v2, v104
	s_waitcnt vmcnt(20)
	v_pk_mul_f32 v[108:109], v[108:109], v[108:109]
	v_pk_mul_f32 v[110:111], v[110:111], v[110:111]
	v_add_f32_e32 v108, v109, v108
	v_add_f32_e32 v110, v110, v111
	v_add_f32_e32 v108, v108, v110
	v_add_f32_e32 v2, v2, v108
	s_waitcnt vmcnt(19)
	v_pk_mul_f32 v[112:113], v[112:113], v[112:113]
	v_pk_mul_f32 v[114:115], v[114:115], v[114:115]
	v_add_f32_e32 v112, v113, v112
	v_add_f32_e32 v114, v114, v115
	v_add_f32_e32 v112, v112, v114
	v_add_f32_e32 v2, v2, v112
	s_waitcnt vmcnt(18)
	v_pk_mul_f32 v[152:153], v[152:153], v[152:153]
	v_pk_mul_f32 v[154:155], v[154:155], v[154:155]
	v_add_f32_e32 v152, v153, v152
	v_add_f32_e32 v154, v154, v155
	v_add_f32_e32 v152, v152, v154
	v_add_f32_e32 v2, v2, v152
	s_waitcnt vmcnt(17)
	v_pk_mul_f32 v[156:157], v[156:157], v[156:157]
	v_pk_mul_f32 v[158:159], v[158:159], v[158:159]
	v_add_f32_e32 v156, v157, v156
	v_add_f32_e32 v158, v158, v159
	v_add_f32_e32 v156, v156, v158
	v_add_f32_e32 v2, v2, v156
	s_waitcnt vmcnt(16)
	v_pk_mul_f32 v[160:161], v[160:161], v[160:161]
	v_pk_mul_f32 v[162:163], v[162:163], v[162:163]
	v_add_f32_e32 v160, v161, v160
	v_add_f32_e32 v162, v162, v163
	v_add_f32_e32 v160, v160, v162
	v_add_f32_e32 v2, v2, v160
	ds_bpermute_b32 v0, v16, v2
	s_waitcnt lgkmcnt(0)
	v_add_f32_e32 v19, v2, v0
	ds_bpermute_b32 v20, v17, v19
	s_waitcnt vmcnt(14)
	v_mfma_f32_16x16x32_bf16 v[0:3], v[196:199], v[164:167], 0
	s_waitcnt vmcnt(12)
	v_mfma_f32_16x16x32_bf16 v[0:3], v[200:203], v[168:171], v[0:3]
	s_waitcnt vmcnt(10)
	v_mfma_f32_16x16x32_bf16 v[0:3], v[220:223], v[172:175], v[0:3]
	s_waitcnt vmcnt(8)
	v_mfma_f32_16x16x32_bf16 v[0:3], v[224:227], v[176:179], v[0:3]
	s_waitcnt vmcnt(6)
	v_mfma_f32_16x16x32_bf16 v[0:3], v[228:231], v[180:183], v[0:3]
	s_waitcnt vmcnt(4)
	v_mfma_f32_16x16x32_bf16 v[0:3], v[132:135], v[184:187], v[0:3]
	s_waitcnt vmcnt(2)
	v_mfma_f32_16x16x32_bf16 v[0:3], v[136:139], v[188:191], v[0:3]
	s_waitcnt vmcnt(0)
	v_mfma_f32_16x16x32_bf16 v[0:3], v[144:147], v[192:195], v[0:3]
	s_waitcnt lgkmcnt(0)
	v_add_f32_e32 v12, v19, v20
	v_fmamk_f32 v12, v12, 0x3b800000, v207
	v_rsq_f32_e32 v12, v12
	s_and_b64 s[0:1], s[0:1], exec
	s_mov_b32 s0, 0xa4400
	s_cselect_b32 s48, s0, 0x9c400
	s_lshl_b32 s0, s4, 6
	v_pk_mul_f32 v[2:3], v[12:13], v[2:3] op_sel_hi:[0,1]
	v_pk_mul_f32 v[0:1], v[12:13], v[0:1] op_sel_hi:[0,1]
	v_lshl_add_u64 v[12:13], v[4:5], 0, s[48:49]
	s_and_b32 s48, s0, 0x7c0
	v_readlane_b32 s0, v253, 39
	v_lshl_add_u64 v[12:13], v[12:13], 0, s[48:49]
	s_add_i32 s4, s4, s84
	s_add_i32 s5, s5, s0
	v_lshl_add_u64 v[12:13], v[12:13], 0, v[148:149]
	s_cmp_gt_i32 s4, 63
	global_store_dwordx4 v[12:13], v[0:3], off
	s_cbranch_scc0 .LBB0_834

.LBB0_1151:
	s_movk_i32 s0, 0xe88
	v_cmp_gt_i32_e32 vcc, s0, v160
	s_and_saveexec_b64 s[0:1], vcc
	v_readlane_b32 s12, v252, 21
	v_readlane_b32 s13, v252, 22
	v_readlane_b32 s16, v252, 25
	v_readlane_b32 s17, v252, 26
	v_readlane_b32 s14, v252, 23
	v_readlane_b32 s15, v252, 24
	s_mov_b32 s12, 0x3fb8aa3b
	v_readlane_b32 s16, v253, 59
	v_readlane_b32 s24, v252, 33
	v_readlane_b32 s25, v252, 34
	v_readlane_b32 s26, v252, 35
	v_readlane_b32 s27, v252, 36
	s_mov_b32 s13, 0x3e38aa3b
	s_mov_b64 s[14:15], 0x100
	v_readlane_b32 s17, v253, 60
	v_readlane_b32 s18, v252, 27
	v_readlane_b32 s19, v252, 28
	v_readlane_b32 s20, v252, 29
	v_readlane_b32 s21, v252, 30
	v_readlane_b32 s22, v252, 31
	v_readlane_b32 s23, v252, 32
	s_cbranch_execz .LBB0_1164
	v_readlane_b32 s6, v253, 57
	v_lshlrev_b32_e32 v0, 2, v160
	v_add_u32_e32 v1, 0x1000, v0
	v_add_u32_e32 v2, 0x2000, v0
	v_add_u32_e32 v3, 0x3000, v0
	v_add_u32_e32 v5, s6, v0
	global_load_dword v62, v0, s[16:17]
	global_load_dword v63, v0, s[16:17] offset:2048
	global_load_dword v64, v1, s[16:17]
	global_load_dword v65, v1, s[16:17] offset:2048
	global_load_dword v66, v2, s[16:17]
	global_load_dword v67, v2, s[16:17] offset:2048
	global_load_dword v68, v3, s[16:17]
	s_movk_i32 s2, 0x88
	v_cmp_gt_u32_e32 vcc, s2, v160
	s_and_saveexec_b64 s[2:3], vcc
	global_load_dword v69, v3, s[16:17] offset:2048
	s_waitcnt vmcnt(0)
	v_mul_f32_e32 v69, 0x3fb8aa3b, v69
	ds_write_b32 v5, v69 offset:14336
	s_or_b64 exec, exec, s[2:3]
	s_waitcnt vmcnt(0)
	v_mul_f32_e32 v62, 0x3fb8aa3b, v62
	ds_write_b32 v5, v62
	v_mul_f32_e32 v63, 0x3fb8aa3b, v63
	ds_write_b32 v5, v63 offset:2048
	v_mul_f32_e32 v64, 0x3fb8aa3b, v64
	ds_write_b32 v5, v64 offset:4096
	v_mul_f32_e32 v65, 0x3fb8aa3b, v65
	ds_write_b32 v5, v65 offset:6144
	v_mul_f32_e32 v66, 0x3fb8aa3b, v66
	ds_write_b32 v5, v66 offset:8192
	v_mul_f32_e32 v67, 0x3fb8aa3b, v67
	ds_write_b32 v5, v67 offset:10240
	v_mul_f32_e32 v68, 0x3fb8aa3b, v68
	ds_write_b32 v5, v68 offset:12288

.LBB0_1168:
	s_or_b64 exec, exec, s[0:1]
	v_readlane_b32 s0, v253, 61
	v_readlane_b32 s1, v253, 62
	v_readlane_b32 s2, v253, 63
	v_readlane_b32 s3, v254, 0
	s_nop 2
	global_load_dword v6, v148, s[0:1]
	s_nop 0
	global_load_dword v4, v148, s[2:3]
	v_max_f32_e32 v3, v3, v3
	s_waitcnt vmcnt(3)
	v_max_f32_e64 v1, |v1|, |v1|
	v_max_f32_e32 v1, v1, v3
	v_and_b32_e32 v3, 64, v210
	v_add_u32_e32 v10, 64, v3
	v_xor_b32_e32 v3, 1, v210
	v_cmp_lt_i32_e32 vcc, v3, v10
	v_max_f32_e32 v2, v2, v2
	s_waitcnt vmcnt(2)
	v_max_f32_e64 v0, |v0|, |v0|
	v_cndmask_b32_e32 v3, v210, v3, vcc
	v_lshlrev_b32_e32 v7, 2, v3
	ds_bpermute_b32 v3, v7, v1
	v_max_f32_e32 v0, v0, v2
	ds_bpermute_b32 v2, v7, v0
	v_or_b32_e32 v159, 64, v158
	s_mov_b32 s6, 2
	s_waitcnt lgkmcnt(1)
	v_max_f32_e32 v3, v3, v3
	v_max_f32_e32 v1, v1, v3
	v_xor_b32_e32 v3, 2, v210
	v_cmp_lt_i32_e32 vcc, v3, v10
	s_waitcnt lgkmcnt(0)
	v_max_f32_e32 v2, v2, v2
	v_max_f32_e32 v0, v0, v2
	v_cndmask_b32_e32 v3, v210, v3, vcc
	v_lshlrev_b32_e32 v5, 2, v3
	ds_bpermute_b32 v3, v5, v1
	ds_bpermute_b32 v2, v5, v0
	v_mov_b32_e32 v16, 0
	s_mov_b64 s[4:5], 0
	v_mov_b32_e32 v18, 0
	s_waitcnt lgkmcnt(1)
	v_max_f32_e32 v3, v3, v3
	v_max_f32_e32 v1, v1, v3
	v_xor_b32_e32 v3, 4, v210
	v_cmp_lt_i32_e32 vcc, v3, v10
	s_waitcnt lgkmcnt(0)
	v_max_f32_e32 v2, v2, v2
	v_max_f32_e32 v0, v0, v2
	v_cndmask_b32_e32 v3, v210, v3, vcc
	v_lshlrev_b32_e32 v3, 2, v3
	ds_bpermute_b32 v8, v3, v1
	ds_bpermute_b32 v2, v3, v0
	s_waitcnt lgkmcnt(1)
	v_max_f32_e32 v8, v8, v8
	v_max_f32_e32 v1, v1, v8
	s_waitcnt lgkmcnt(0)
	v_max_f32_e32 v8, v2, v2
	v_xor_b32_e32 v2, 8, v210
	v_cmp_lt_i32_e32 vcc, v2, v10
	v_max_f32_e32 v0, v0, v8
	s_nop 0
	v_cndmask_b32_e32 v2, v210, v2, vcc
	v_lshlrev_b32_e32 v2, 2, v2
	ds_bpermute_b32 v9, v2, v1
	ds_bpermute_b32 v8, v2, v0
	s_waitcnt lgkmcnt(1)
	v_max_f32_e32 v9, v9, v9
	v_max_f32_e32 v1, v1, v9
	v_xor_b32_e32 v9, 16, v210
	v_cmp_lt_i32_e32 vcc, v9, v10
	s_waitcnt lgkmcnt(0)
	v_max_f32_e32 v8, v8, v8
	v_max_f32_e32 v0, v0, v8
	v_cndmask_b32_e32 v9, v210, v9, vcc
	v_lshlrev_b32_e32 v217, 2, v9
	ds_bpermute_b32 v9, v217, v1
	ds_bpermute_b32 v8, v217, v0
	s_waitcnt lgkmcnt(1)
	v_max_f32_e32 v9, v9, v9
	v_max_f32_e32 v9, v1, v9
	s_waitcnt lgkmcnt(0)
	v_max_f32_e32 v1, v8, v8
	v_max_f32_e32 v8, v0, v1
	v_xor_b32_e32 v0, 32, v210
	v_cmp_lt_i32_e32 vcc, v0, v10
	s_nop 1
	v_cndmask_b32_e32 v0, v210, v0, vcc
	v_lshlrev_b32_e32 v218, 2, v0
	ds_bpermute_b32 v11, v218, v9
	ds_bpermute_b32 v10, v218, v8
	v_sub_u32_e32 v0, 0xe87, v158
	v_lshrrev_b32_e32 v0, 6, v0
	v_add_u32_e32 v13, 1, v0
	v_and_b32_e32 v12, 62, v13
	v_lshlrev_b32_e32 v34, 2, v158
	v_add_u32_e32 v35, 0x1000, v34
	v_add_u32_e32 v36, 0x2000, v34
	v_add_u32_e32 v37, 0x3000, v34
	v_add_u32_e32 v38, 0xe80, v158
	v_min_u32_e32 v38, 0xe87, v38
	v_lshlrev_b32_e32 v38, 2, v38
	global_load_dword v62, v34, s[16:17]
	global_load_dword v63, v34, s[16:17] offset:256
	global_load_dword v64, v34, s[16:17] offset:512
	global_load_dword v65, v34, s[16:17] offset:768
	global_load_dword v66, v34, s[16:17] offset:1024
	global_load_dword v67, v34, s[16:17] offset:1280
	global_load_dword v68, v34, s[16:17] offset:1536
	global_load_dword v69, v34, s[16:17] offset:1792
	global_load_dword v70, v34, s[16:17] offset:2048
	global_load_dword v71, v34, s[16:17] offset:2304
	global_load_dword v72, v34, s[16:17] offset:2560
	global_load_dword v73, v34, s[16:17] offset:2816
	global_load_dword v74, v34, s[16:17] offset:3072
	global_load_dword v75, v34, s[16:17] offset:3328
	global_load_dword v76, v34, s[16:17] offset:3584
	global_load_dword v77, v34, s[16:17] offset:3840
	global_load_dword v78, v35, s[16:17]
	global_load_dword v79, v35, s[16:17] offset:256
	global_load_dword v80, v35, s[16:17] offset:512
	global_load_dword v81, v35, s[16:17] offset:768
	global_load_dword v82, v35, s[16:17] offset:1024
	global_load_dword v83, v35, s[16:17] offset:1280
	global_load_dword v84, v35, s[16:17] offset:1536
	global_load_dword v85, v35, s[16:17] offset:1792
	global_load_dword v86, v35, s[16:17] offset:2048
	global_load_dword v87, v35, s[16:17] offset:2304
	global_load_dword v88, v35, s[16:17] offset:2560
	global_load_dword v89, v35, s[16:17] offset:2816
	global_load_dword v90, v35, s[16:17] offset:3072
	global_load_dword v91, v35, s[16:17] offset:3328
	global_load_dword v92, v35, s[16:17] offset:3584
	global_load_dword v93, v35, s[16:17] offset:3840
	global_load_dword v94, v36, s[16:17]
	global_load_dword v95, v36, s[16:17] offset:256
	global_load_dword v96, v36, s[16:17] offset:512
	global_load_dword v97, v36, s[16:17] offset:768
	global_load_dword v98, v36, s[16:17] offset:1024
	global_load_dword v99, v36, s[16:17] offset:1280
	global_load_dword v100, v36, s[16:17] offset:1536
	global_load_dword v101, v36, s[16:17] offset:1792
	global_load_dword v102, v36, s[16:17] offset:2048
	global_load_dword v103, v36, s[16:17] offset:2304
	global_load_dword v104, v36, s[16:17] offset:2560
	global_load_dword v105, v36, s[16:17] offset:2816
	global_load_dword v106, v36, s[16:17] offset:3072
	global_load_dword v107, v36, s[16:17] offset:3328
	global_load_dword v108, v36, s[16:17] offset:3584
	global_load_dword v109, v36, s[16:17] offset:3840
	global_load_dword v110, v37, s[16:17]
	global_load_dword v111, v37, s[16:17] offset:256
	global_load_dword v112, v37, s[16:17] offset:512
	global_load_dword v113, v37, s[16:17] offset:768
	global_load_dword v114, v37, s[16:17] offset:1024
	global_load_dword v115, v37, s[16:17] offset:1280
	global_load_dword v161, v37, s[16:17] offset:1536
	global_load_dword v162, v37, s[16:17] offset:1792
	global_load_dword v163, v37, s[16:17] offset:2048
	global_load_dword v164, v37, s[16:17] offset:2304
	global_load_dword v165, v38, s[16:17]
	s_waitcnt vmcnt(0)
	v_max_f32_e64 v14, |v62|, |v63|
	v_max_f32_e64 v14, v14, |v64|
	v_max_f32_e64 v14, v14, |v65|
	v_max_f32_e64 v14, v14, |v66|
	v_max_f32_e64 v14, v14, |v67|
	v_max_f32_e64 v14, v14, |v68|
	v_max_f32_e64 v14, v14, |v69|
	v_max_f32_e64 v14, v14, |v70|
	v_max_f32_e64 v14, v14, |v71|
	v_max_f32_e64 v14, v14, |v72|
	v_max_f32_e64 v14, v14, |v73|
	v_max_f32_e64 v14, v14, |v74|
	v_max_f32_e64 v14, v14, |v75|
	v_max_f32_e64 v14, v14, |v76|
	v_max_f32_e64 v14, v14, |v77|
	v_max_f32_e64 v14, v14, |v78|
	v_max_f32_e64 v14, v14, |v79|
	v_max_f32_e64 v14, v14, |v80|
	v_max_f32_e64 v14, v14, |v81|
	v_max_f32_e64 v14, v14, |v82|
	v_max_f32_e64 v14, v14, |v83|
	v_max_f32_e64 v14, v14, |v84|
	v_max_f32_e64 v14, v14, |v85|
	v_max_f32_e64 v14, v14, |v86|
	v_max_f32_e64 v14, v14, |v87|
	v_max_f32_e64 v14, v14, |v88|
	v_max_f32_e64 v14, v14, |v89|
	v_max_f32_e64 v14, v14, |v90|
	v_max_f32_e64 v14, v14, |v91|
	v_max_f32_e64 v14, v14, |v92|
	v_max_f32_e64 v14, v14, |v93|
	v_max_f32_e64 v14, v14, |v94|
	v_max_f32_e64 v14, v14, |v95|
	v_max_f32_e64 v14, v14, |v96|
	v_max_f32_e64 v14, v14, |v97|
	v_max_f32_e64 v14, v14, |v98|
	v_max_f32_e64 v14, v14, |v99|
	v_max_f32_e64 v14, v14, |v100|
	v_max_f32_e64 v14, v14, |v101|
	v_max_f32_e64 v14, v14, |v102|
	v_max_f32_e64 v14, v14, |v103|
	v_max_f32_e64 v14, v14, |v104|
	v_max_f32_e64 v14, v14, |v105|
	v_max_f32_e64 v14, v14, |v106|
	v_max_f32_e64 v14, v14, |v107|
	v_max_f32_e64 v14, v14, |v108|
	v_max_f32_e64 v14, v14, |v109|
	v_max_f32_e64 v14, v14, |v110|
	v_max_f32_e64 v14, v14, |v111|
	v_max_f32_e64 v14, v14, |v112|
	v_max_f32_e64 v14, v14, |v113|
	v_max_f32_e64 v14, v14, |v114|
	v_max_f32_e64 v14, v14, |v115|
	v_max_f32_e64 v14, v14, |v161|
	v_max_f32_e64 v14, v14, |v162|
	v_max_f32_e64 v14, v14, |v163|
	v_max_f32_e64 v14, v14, |v164|
	v_max_f32_e64 v14, v14, |v165|
